# P7a stage 1: reciprocal via v_rcp_f32 instead of the 11-instruction IEEE division sequence
# baseline (speedup 1.0000x reference)
; #define BAR_LDS() do { asm volatile("s_waitcnt lgkmcnt(0)" ::: "memory"); __builtin_amdgcn_s_barrier(); asm volatile("" ::: "memory"); } while (0)
; __device__ __forceinline__ unsigned pk2(float lo, float hi) { const f32x2c v = {lo, hi}; const bf16x2c b = __builtin_convertvector(v, bf16x2c); return __builtin_bit_cast(unsigned, b); }
; __device__ __forceinline__ void chunk_pre(const Params& p, LAS unsigned char* lds, int item, int next_item, int tid, int wave, int lane, h16 (&raw)[48]) {
;     ...
;         const int g = tid >> 6, k = tid & 63;
;         float wv[8], lp[8];
; #pragma unroll
;         for (int i = 0; i < 8; ++i) wv[i] = (float)raw[i * 6 + 2];
;         lp[0] = wv[0];
; #pragma unroll
;         for (int i = 1; i < 8; ++i) lp[i] = lp[i - 1] * wv[i];
;         GT[g * 64 + k] = lp[7];
;         BAR_LDS();
;         float bs = 1.f, WL = 1.f;
; #pragma unroll
;         for (int q = 0; q < 8; ++q) { const float gq = GT[q * 64 + k]; if (q < g) bs *= gq; WL *= gq; }
;         float bhv[8], khv[8], vtv[8], atv[8];
; #pragma unroll
;         for (int i = 0; i < 8; ++i) {
;             const int t = 8 * g + i;
;             const float kk = (float)raw[i * 6 + 0], wr = (float)raw[i * 6 + 1], bb = (float)raw[i * 6 + 3], kx = (float)raw[i * 6 + 4], vv = (float)raw[i * 6 + 5];
;             const float Wt = bs * lp[i], Wp = (i == 0) ? bs : bs * lp[i - 1], iW = 1.f / Wt;
;             atv[i] = -kk * Wp; At[t * MS + k] = (bf16_t)(pk2(-kk * Wp, 0.f) & 0xffffu); Rt[t * MS + k] = (bf16_t)(pk2(wr * Wp, 0.f) & 0xffffu);
;             Bt[t * MS + k] = (bf16_t)(pk2(bb * iW, 0.f) & 0xffffu); Kt[t * MS + k] = (bf16_t)(pk2(kx * iW, 0.f) & 0xffffu);
;             bhv[i] = bb * iW * WL; khv[i] = kx * iW * WL; vtv[i] = vv;
.LBB0_923:
	s_waitcnt vmcnt(45)
	v_cvt_f32_f16_e32 v10, v42
	s_waitcnt vmcnt(39)
	v_cvt_f32_f16_e32 v4, v48
	s_waitcnt vmcnt(33)
	v_cvt_f32_f16_e32 v5, v54
	s_waitcnt vmcnt(27)
	v_cvt_f32_f16_e32 v6, v60
	s_waitcnt vmcnt(21)
	v_cvt_f32_f16_e32 v12, v68
	s_waitcnt vmcnt(15)
	v_cvt_f32_f16_e32 v13, v75
	v_mul_f32_e32 v11, v10, v4
	s_waitcnt vmcnt(9)
	v_cvt_f32_f16_e32 v14, v83
	v_mul_f32_e32 v34, v11, v5
	s_waitcnt vmcnt(3)
	v_cvt_f32_f16_e32 v15, v89
	v_mul_f32_e32 v35, v34, v6
	v_mul_f32_e32 v12, v35, v12
	v_mul_f32_e32 v13, v12, v13
	v_mul_f32_e32 v4, v13, v14
	v_mul_f32_e32 v5, v4, v15
	ds_write_b32 v63, v5
	s_waitcnt lgkmcnt(0)
	s_barrier
	ds_read2st64_b32 v[14:15], v65 offset1:1
	ds_read2st64_b32 v[220:221], v65 offset0:2 offset1:3
	ds_read2st64_b32 v[222:223], v65 offset0:4 offset1:5
	ds_read2st64_b32 v[224:225], v65 offset0:6 offset1:7
	v_readlane_b32 s14, v244, 33
	v_readlane_b32 s15, v244, 34
	v_cvt_f32_f16_e64 v37, -v40
	v_cvt_f32_f16_e32 v36, v41
	s_waitcnt lgkmcnt(3)
	v_cndmask_b32_e64 v6, 1.0, v14, s[82:83]
	v_mul_f32_e32 v16, v6, v15
	v_cndmask_b32_e64 v6, v6, v16, s[14:15]
	v_mul_f32_e32 v16, v14, v15
	s_nop 0
	v_readlane_b32 s14, v244, 35
	v_readlane_b32 s15, v244, 36
	v_cvt_f32_f16_e32 v17, v51
	v_cvt_f32_f16_e64 v170, -v46
	s_waitcnt lgkmcnt(2)
	v_mul_f32_e32 v168, v220, v6
	v_cndmask_b32_e64 v6, v6, v168, s[14:15]
	v_readlane_b32 s14, v244, 37
	v_mul_f32_e32 v14, v16, v220
	v_mul_f32_e32 v16, v221, v6
	v_readlane_b32 s15, v244, 38
	v_cvt_f32_f16_e32 v171, v47
	v_cvt_f32_f16_e32 v174, v53
	v_cndmask_b32_e64 v6, v6, v16, s[14:15]
	v_mul_f32_e32 v16, v14, v221
	s_nop 0
	v_readlane_b32 s14, v244, 39
	v_readlane_b32 s15, v244, 40
	v_cvt_f32_f16_e32 v18, v55
	v_cvt_f32_f16_e32 v19, v61
	s_waitcnt lgkmcnt(1)
	v_mul_f32_e32 v168, v222, v6
	v_cndmask_b32_e64 v6, v6, v168, s[14:15]
	v_readlane_b32 s14, v244, 41
	v_mul_f32_e32 v14, v16, v222
	v_mul_f32_e32 v16, v223, v6
	v_readlane_b32 s15, v244, 42
	v_cvt_f32_f16_e32 v176, v59
	v_cvt_f32_f16_e32 v177, v67
	v_cndmask_b32_e64 v6, v6, v16, s[14:15]
	v_mul_f32_e32 v16, v14, v223
	s_nop 0
	v_readlane_b32 s14, v244, 43
	v_readlane_b32 s15, v244, 44
	v_cvt_f32_f16_e32 v169, v73
	v_cvt_f32_f16_e32 v8, v69
	s_waitcnt lgkmcnt(0)
	v_mul_f32_e32 v168, v224, v6
	v_cndmask_b32_e64 v6, v6, v168, s[14:15]
	v_readlane_b32 s14, v244, 45
	v_mul_f32_e32 v14, v16, v224
	v_mul_f32_e32 v16, v225, v6
	v_readlane_b32 s15, v244, 46
	v_cvt_f32_f16_e32 v9, v76
	v_cvt_f32_f16_e32 v7, v45
	v_cndmask_b32_e64 v16, v6, v16, s[14:15]
	v_mul_f32_e32 v168, v16, v37
	v_mul_f32_e32 v6, v14, v225
	v_cvt_pk_bf16_f32 v14, v168, s0
	ds_write_b16 v74, v14
	v_mul_f32_e32 v14, v16, v36
	v_pk_mul_f32 v[36:37], v[16:17], v[10:11] op_sel_hi:[0,1]
	v_cvt_pk_bf16_f32 v14, v14, s0
	ds_write_b16 v74, v14 offset:27648
	v_cvt_f32_f16_e32 v14, v43
	v_rcp_f32_e32 v173, v37
	v_cvt_f32_f16_e32 v15, v49
	v_mul_f32_e32 v170, v36, v170
	v_pk_mul_f32 v[12:13], v[12:13], v[16:17] op_sel_hi:[1,0]
	v_rcp_f32_e32 v172, v36
	s_nop 0
	v_pk_mul_f32 v[10:11], v[172:173], v[14:15]
	v_cvt_f32_f16_e32 v15, v50
	v_cvt_pk_bf16_f32 v14, v10, s0
	ds_write_b16 v74, v14 offset:9216
	v_cvt_pk_bf16_f32 v14, v170, s0
	ds_write_b16 v74, v14 offset:144
	v_mul_f32_e32 v14, v36, v171
	v_cvt_pk_bf16_f32 v14, v14, s0
	ds_write_b16 v74, v14 offset:27792
	v_cvt_pk_bf16_f32 v14, v11, s0
	ds_write_b16 v74, v14 offset:9360
	v_cvt_f32_f16_e32 v14, v44
	v_mul_f32_e32 v169, v12, v169
	v_cvt_pk_bf16_f32 v169, v169, s0
	ds_write_b16 v74, v169 offset:28368
	v_pk_mul_f32 v[14:15], v[172:173], v[14:15]
	v_pk_mul_f32 v[172:173], v[34:35], v[16:17] op_sel_hi:[1,0]
	v_cvt_pk_bf16_f32 v171, v14, s0
	ds_write_b16 v74, v171 offset:18432
	v_cvt_pk_bf16_f32 v171, v15, s0
	ds_write_b16 v74, v171 offset:18576
	v_mul_f32_e32 v171, v37, v174
	v_cvt_pk_bf16_f32 v171, v171, s0
	ds_write_b16 v74, v171 offset:27936
	v_rcp_f32_e32 v175, v173
	v_pk_mov_b32 v[36:37], v[36:37], v[172:173] op_sel:[1,0]
	v_cvt_f32_f16_e32 v167, v82
	v_pk_mul_f32 v[4:5], v[4:5], v[16:17] op_sel_hi:[1,0]
	v_rcp_f32_e32 v174, v172
	s_nop 0
	v_pk_mul_f32 v[34:35], v[174:175], v[18:19]
	v_cvt_f32_f16_e64 v19, -v58
	v_cvt_pk_bf16_f32 v18, v34, s0
	ds_write_b16 v74, v18 offset:9504
	v_cvt_f32_f16_e64 v18, -v52
	v_cvt_f32_f16_e32 v166, v88
	v_pk_mul_f32 v[18:19], v[36:37], v[18:19]
	v_cvt_f32_f16_e32 v37, v62
	v_cvt_pk_bf16_f32 v36, v18, s0
	ds_write_b16 v74, v36 offset:288
	v_cvt_pk_bf16_f32 v36, v19, s0
	ds_write_b16 v74, v36 offset:432
	v_mul_f32_e32 v36, v172, v176
	v_cvt_pk_bf16_f32 v36, v36, s0
	ds_write_b16 v74, v36 offset:28080
	v_cvt_pk_bf16_f32 v36, v35, s0
	ds_write_b16 v74, v36 offset:9648
	v_cvt_f32_f16_e32 v36, v56
	v_cvt_f32_f16_e64 v180, -v81
	v_cvt_f32_f16_e64 v181, -v87
	v_cvt_f32_f16_e32 v20, v57
	v_pk_mul_f32 v[36:37], v[174:175], v[36:37]
	v_cvt_f32_f16_e32 v38, v64
	v_cvt_pk_bf16_f32 v171, v36, s0
	ds_write_b16 v74, v171 offset:18720
	v_cvt_pk_bf16_f32 v171, v37, s0
	ds_write_b16 v74, v171 offset:18864
	v_mul_f32_e32 v171, v173, v177
	v_cvt_pk_bf16_f32 v171, v171, s0
	ds_write_b16 v74, v171 offset:28224
	v_pk_mov_b32 v[172:173], v[172:173], v[12:13] op_sel:[1,0]
	v_cvt_f32_f16_e32 v39, v71
	v_cvt_f32_f16_e32 v163, v80
	v_rcp_f32_e32 v175, v13
	v_cvt_f32_f16_e32 v164, v86
	s_waitcnt vmcnt(0)
; #define LAS __attribute__((address_space(3)))
; __device__ __forceinline__ unsigned pk2(float lo, float hi) { const f32x2c v = {lo, hi}; const bf16x2c b = __builtin_convertvector(v, bf16x2c); return __builtin_bit_cast(unsigned, b); }
; __device__ __forceinline__ void chunk_pre(const Params& p, LAS unsigned char* lds, int item, int next_item, int tid, int wave, int lane, h16 (&raw)[48]) {
;     ...
;         for (int i = 0; i < 8; ++i) {
;             const int t = 8 * g + i;
;             const float kk = (float)raw[i * 6 + 0], wr = (float)raw[i * 6 + 1], bb = (float)raw[i * 6 + 3], kx = (float)raw[i * 6 + 4], vv = (float)raw[i * 6 + 5];
;             const float Wt = bs * lp[i], Wp = (i == 0) ? bs : bs * lp[i - 1], iW = 1.f / Wt;
;             atv[i] = -kk * Wp; At[t * MS + k] = (bf16_t)(pk2(-kk * Wp, 0.f) & 0xffffu); Rt[t * MS + k] = (bf16_t)(pk2(wr * Wp, 0.f) & 0xffffu);
;             Bt[t * MS + k] = (bf16_t)(pk2(bb * iW, 0.f) & 0xffffu); Kt[t * MS + k] = (bf16_t)(pk2(kx * iW, 0.f) & 0xffffu);
;             bhv[i] = bb * iW * WL; khv[i] = kx * iW * WL; vtv[i] = vv;
;         }
;         *(LAS u32x4*)(BhT + k * MS + 8 * g) = (u32x4){pk2(bhv[0], bhv[1]), pk2(bhv[2], bhv[3]), pk2(bhv[4], bhv[5]), pk2(bhv[6], bhv[7])};
;         *(LAS u32x4*)(KhT + k * MS + 8 * g) = (u32x4){pk2(khv[0], khv[1]), pk2(khv[2], khv[3]), pk2(khv[4], khv[5]), pk2(khv[6], khv[7])};
;         *(LAS u32x4*)(VT + k * MS + 8 * g) = (u32x4){pk2(vtv[0], vtv[1]), pk2(vtv[2], vtv[3]), pk2(vtv[4], vtv[5]), pk2(vtv[6], vtv[7])};
;         *(LAS u32x4*)(AtT + k * MS + 8 * g) = (u32x4){pk2(atv[0], atv[1]), pk2(atv[2], atv[3]), pk2(atv[4], atv[5]), pk2(atv[6], atv[7])};
;     }
;     if (next_item >= 0) chunk_load(p, next_item, tid, raw);
	v_cvt_f32_f16_e32 v165, v93
	s_add_i32 s50, s45, s94
	v_cvt_f32_f16_e64 v176, -v66
	v_cvt_f32_f16_e64 v177, -v72
	v_rcp_f32_e32 v174, v12
	s_nop 0
	v_pk_mul_f32 v[8:9], v[174:175], v[8:9]
	s_cmpk_gt_i32 s50, 0xfff
	v_cvt_pk_bf16_f32 v171, v8, s0
	v_pk_mul_f32 v[172:173], v[172:173], v[176:177]
	v_cvt_pk_bf16_f32 v169, v9, s0
	v_pk_mul_f32 v[176:177], v[6:7], v[8:9] op_sel_hi:[0,1]
	v_cvt_f32_f16_e32 v8, v70
	v_cvt_f32_f16_e32 v9, v78
	ds_write_b16 v74, v169 offset:9936
	ds_write_b16 v74, v171 offset:9792
	v_cvt_pk_bf16_f32 v171, v172, s0
	v_pk_mul_f32 v[8:9], v[174:175], v[8:9]
	ds_write_b16 v74, v171 offset:576
	v_cvt_pk_bf16_f32 v169, v8, s0
	v_pk_mul_f32 v[174:175], v[6:7], v[8:9] op_sel_hi:[0,1]
	v_mul_f32_e32 v8, v13, v167
	ds_write_b16 v74, v169 offset:19008
	v_cvt_pk_bf16_f32 v169, v9, s0
	ds_write_b16 v74, v169 offset:19152
	v_cvt_pk_bf16_f32 v171, v173, s0
	ds_write_b16 v74, v171 offset:720
	v_rcp_f32_e32 v179, v5
	v_cvt_pk_bf16_f32 v8, v8, s0
	ds_write_b16 v74, v8 offset:28512
	v_cvt_f32_f16_e32 v8, v84
	v_cvt_f32_f16_e32 v9, v90
	v_pk_mov_b32 v[12:13], v[12:13], v[4:5] op_sel:[1,0]
	v_rcp_f32_e32 v178, v4
	v_pk_mul_f32 v[12:13], v[12:13], v[180:181]
	v_mul_f32_e32 v4, v4, v166
	v_pk_mul_f32 v[8:9], v[178:179], v[8:9]
	v_cvt_pk_bf16_f32 v5, v12, s0
	v_cvt_pk_bf16_f32 v4, v4, s0
	ds_write_b16 v74, v5 offset:864
	v_cvt_pk_bf16_f32 v5, v13, s0
	ds_write_b16 v74, v4 offset:28656
	v_cvt_pk_bf16_f32 v4, v9, s0
	v_cvt_pk_bf16_f32 v16, v8, s0
	ds_write_b16 v74, v5 offset:1008
	ds_write_b16 v74, v4 offset:10224
	v_pk_mul_f32 v[4:5], v[6:7], v[8:9] op_sel_hi:[0,1]
	v_cvt_f32_f16_e32 v8, v85
	v_cvt_f32_f16_e32 v9, v92
	s_cselect_b64 s[10:11], -1, 0
	s_cmpk_lt_i32 s50, 0x1000
	v_pk_mul_f32 v[10:11], v[6:7], v[10:11] op_sel_hi:[0,1]
	v_pk_mul_f32 v[8:9], v[178:179], v[8:9]
	v_pk_mul_f32 v[34:35], v[6:7], v[34:35] op_sel_hi:[0,1]
	ds_write_b16 v74, v16 offset:10080
	v_cvt_pk_bf16_f32 v16, v8, s0
	s_cselect_b32 s12, s50, -1
	v_pk_mul_f32 v[14:15], v[6:7], v[14:15] op_sel_hi:[0,1]
	v_pk_mul_f32 v[36:37], v[6:7], v[36:37] op_sel_hi:[0,1]
	ds_write_b16 v74, v16 offset:19296
	v_cvt_pk_bf16_f32 v16, v9, s0
	v_pk_mul_f32 v[166:167], v[6:7], v[8:9] op_sel_hi:[0,1]
	v_cvt_pk_bf16_f32 v8, v10, v11
	v_cvt_pk_bf16_f32 v9, v34, v35
	v_cvt_pk_bf16_f32 v10, v176, v177
	v_cvt_pk_bf16_f32 v11, v4, v5
	v_cvt_pk_bf16_f32 v4, v7, v17
	v_cvt_pk_bf16_f32 v5, v20, v38
	v_cvt_pk_bf16_f32 v6, v39, v163
	v_cvt_pk_bf16_f32 v7, v164, v165
	ds_write_b16 v74, v16 offset:19440
	ds_write_b128 v77, v[8:11] offset:36864
	v_cvt_pk_bf16_f32 v8, v14, v15
	v_cvt_pk_bf16_f32 v9, v36, v37
	v_cvt_pk_bf16_f32 v10, v174, v175
	v_cvt_pk_bf16_f32 v11, v166, v167
	ds_write_b128 v77, v[4:7] offset:55296
	v_cvt_pk_bf16_f32 v4, v168, v170
	v_cvt_pk_bf16_f32 v5, v18, v19
	v_cvt_pk_bf16_f32 v6, v172, v173
	v_cvt_pk_bf16_f32 v7, v12, v13
	s_cmp_lt_i32 s12, 0
	ds_write_b128 v77, v[8:11] offset:46080
	ds_write_b128 v79, v[4:7]
	s_cbranch_scc1 .LBB0_925
	s_lshr_b32 s8, s12, 7
	s_lshl_b64 s[14:15], s[8:9], 13
	s_lshl_b32 s8, s12, 6
	s_and_b32 s8, s8, 0x1fc0
	s_or_b32 s8, s14, s8
	v_mad_u64_u32 v[4:5], s[12:13], s8, v160, v[22:23]
	s_mul_i32 s8, s15, 0x300
	v_add_u32_e32 v5, s8, v5
	global_load_ushort v40, v[4:5], off
	global_load_ushort v41, v[4:5], off offset:128
	global_load_ushort v42, v[4:5], off offset:256
	global_load_ushort v43, v[4:5], off offset:384
	global_load_ushort v44, v[4:5], off offset:512
	global_load_ushort v45, v[4:5], off offset:640
	global_load_ushort v46, v[4:5], off offset:768
	global_load_ushort v47, v[4:5], off offset:896
	global_load_ushort v48, v[4:5], off offset:1024
	global_load_ushort v49, v[4:5], off offset:1152
	global_load_ushort v50, v[4:5], off offset:1280
	global_load_ushort v51, v[4:5], off offset:1408
	global_load_ushort v52, v[4:5], off offset:1536
	global_load_ushort v53, v[4:5], off offset:1664
	global_load_ushort v54, v[4:5], off offset:1792
	global_load_ushort v55, v[4:5], off offset:1920
	global_load_ushort v56, v[4:5], off offset:2048
	global_load_ushort v57, v[4:5], off offset:2176
	global_load_ushort v58, v[4:5], off offset:2304
	global_load_ushort v59, v[4:5], off offset:2432
	global_load_ushort v60, v[4:5], off offset:2560
	global_load_ushort v61, v[4:5], off offset:2688
	global_load_ushort v62, v[4:5], off offset:2816
	global_load_ushort v64, v[4:5], off offset:2944
	global_load_ushort v66, v[4:5], off offset:3072
	global_load_ushort v67, v[4:5], off offset:3200
	global_load_ushort v68, v[4:5], off offset:3328
	global_load_ushort v69, v[4:5], off offset:3456
	global_load_ushort v70, v[4:5], off offset:3584
	global_load_ushort v71, v[4:5], off offset:3712
	global_load_ushort v72, v[4:5], off offset:3840
	global_load_ushort v73, v[4:5], off offset:3968
	v_add_co_u32_e32 v4, vcc, s53, v4
	s_nop 1
	v_addc_co_u32_e32 v5, vcc, 0, v5, vcc
	global_load_ushort v75, v[4:5], off
	global_load_ushort v76, v[4:5], off offset:128
	global_load_ushort v78, v[4:5], off offset:256
	global_load_ushort v80, v[4:5], off offset:384
	global_load_ushort v81, v[4:5], off offset:512
	global_load_ushort v82, v[4:5], off offset:640
	global_load_ushort v83, v[4:5], off offset:768
	global_load_ushort v84, v[4:5], off offset:896
	global_load_ushort v85, v[4:5], off offset:1024
	global_load_ushort v86, v[4:5], off offset:1152
	global_load_ushort v87, v[4:5], off offset:1280
	global_load_ushort v88, v[4:5], off offset:1408
	global_load_ushort v89, v[4:5], off offset:1536
	global_load_ushort v90, v[4:5], off offset:1664
	global_load_ushort v92, v[4:5], off offset:1792
	global_load_ushort v93, v[4:5], off offset:1920
